# S5: carried-state bf16 rows stored 16*(row&15) bytes into their 512-B row (scan unrolled x2, static offsets) so the output-GEMM fragment reads of 16 rows hit 16 different bank groups instead of one
# speedup vs baseline: 1.1241x; 1.0039x over previous
.LBB0_495:
	s_waitcnt lgkmcnt(0)
	s_barrier
	ds_read_b128 v[212:215], v197
	ds_read_b128 v[216:219], v198
	ds_read_b128 v[220:223], v199
	ds_read_b128 v[228:231], v200
	ds_read_b128 v[232:235], v201
	s_waitcnt vmcnt(23)
	s_waitcnt lgkmcnt(4)
	v_mfma_f32_16x16x32_bf16 v[36:39], v[136:139], v[212:215], 0
	s_add_i32 s0, 0, 0x10000
	v_add3_u32 v184, s0, v196, v184
	v_lshl_add_u32 v184, v182, 4, v184
	v_lshlrev_b32_e32 v205, 3, v156
	s_waitcnt vmcnt(11)
	v_mfma_f32_16x16x32_bf16 v[32:35], v[152:155], v[212:215], 0
	s_ashr_i32 s22, s51, 5
	s_ashr_i32 s23, s22, 31
	s_lshl_b32 s0, s45, 20
	ds_read_b128 v[236:239], v202
	s_waitcnt lgkmcnt(4)
	v_mfma_f32_16x16x32_bf16 v[36:39], v[120:123], v[216:219], v[36:39]
	s_add_u32 s0, s16, s0
	s_addc_u32 s26, s17, 0
	s_lshl_b64 s[22:23], s[22:23], 16
	s_waitcnt vmcnt(10)
	v_mfma_f32_16x16x32_bf16 v[32:35], v[148:151], v[216:219], v[32:35]
	s_add_u32 s22, s0, s22
	s_addc_u32 s23, s26, s23
	ds_read_b128 v[240:243], v203
	s_waitcnt lgkmcnt(4)
	v_mfma_f32_16x16x32_bf16 v[36:39], v[108:111], v[220:223], v[36:39]
	s_add_i32 s43, s43, 1
	s_mov_b32 s51, s44
	s_waitcnt vmcnt(9)
	v_mfma_f32_16x16x32_bf16 v[32:35], v[144:147], v[220:223], v[32:35]
	ds_read_b128 v[244:247], v204
	s_waitcnt lgkmcnt(4)
	v_mfma_f32_16x16x32_bf16 v[36:39], v[100:103], v[228:231], v[36:39]
	s_waitcnt vmcnt(8)
	v_mfma_f32_16x16x32_bf16 v[32:35], v[140:143], v[228:231], v[32:35]
	ds_read_b128 v[212:215], v184
	s_waitcnt lgkmcnt(4)
	v_mfma_f32_16x16x32_bf16 v[36:39], v[92:95], v[232:235], v[36:39]
	s_waitcnt vmcnt(7)
	v_mfma_f32_16x16x32_bf16 v[32:35], v[132:135], v[232:235], v[32:35]
	ds_read_b128 v[216:219], v184 offset:64
	s_waitcnt lgkmcnt(4)
	v_mfma_f32_16x16x32_bf16 v[36:39], v[84:87], v[236:239], v[36:39]
	s_waitcnt vmcnt(6)
	v_mfma_f32_16x16x32_bf16 v[32:35], v[128:131], v[236:239], v[32:35]
	ds_read_b128 v[220:223], v184 offset:128
	s_waitcnt lgkmcnt(4)
	v_mfma_f32_16x16x32_bf16 v[36:39], v[80:83], v[240:243], v[36:39]
	s_waitcnt vmcnt(5)
	v_mfma_f32_16x16x32_bf16 v[32:35], v[124:127], v[240:243], v[32:35]
	ds_read_b128 v[228:231], v184 offset:192
	s_waitcnt lgkmcnt(4)
	v_mfma_f32_16x16x32_bf16 v[36:39], v[76:79], v[244:247], v[36:39]
	s_waitcnt vmcnt(4)
	v_mfma_f32_16x16x32_bf16 v[32:35], v[116:119], v[244:247], v[32:35]
	ds_read_b128 v[232:235], v197 offset:8192
	s_waitcnt lgkmcnt(4)
	v_mfma_f32_16x16x32_bf16 v[36:39], v[72:75], v[212:215], v[36:39]
	s_waitcnt vmcnt(3)
	v_mfma_f32_16x16x32_bf16 v[32:35], v[112:115], v[212:215], v[32:35]
	ds_read_b128 v[236:239], v198 offset:8192
	s_waitcnt lgkmcnt(4)
	v_mfma_f32_16x16x32_bf16 v[36:39], v[68:71], v[216:219], v[36:39]
	s_waitcnt vmcnt(2)
	v_mfma_f32_16x16x32_bf16 v[32:35], v[104:107], v[216:219], v[32:35]
	ds_read_b128 v[240:243], v199 offset:8192
	s_waitcnt lgkmcnt(4)
	v_mfma_f32_16x16x32_bf16 v[36:39], v[64:67], v[220:223], v[36:39]
	s_waitcnt vmcnt(1)
	v_mfma_f32_16x16x32_bf16 v[32:35], v[96:99], v[220:223], v[32:35]
	ds_read_b128 v[244:247], v200 offset:8192
	s_waitcnt lgkmcnt(4)
	v_mfma_f32_16x16x32_bf16 v[156:159], v[40:43], v[228:231], v[36:39]
	s_nop 2
	s_waitcnt vmcnt(0)
	v_mfma_f32_16x16x32_bf16 v[32:35], v[88:91], v[228:231], v[32:35]
	ds_read_b128 v[212:215], v201 offset:8192
	s_waitcnt lgkmcnt(4)
	v_mfma_f32_16x16x32_bf16 v[44:47], v[136:139], v[232:235], 0
	v_mfma_f32_16x16x32_bf16 v[36:39], v[152:155], v[232:235], 0
	ds_read_b128 v[216:219], v202 offset:8192
	s_waitcnt lgkmcnt(4)
	v_mfma_f32_16x16x32_bf16 v[44:47], v[120:123], v[236:239], v[44:47]
	v_mfma_f32_16x16x32_bf16 v[36:39], v[148:151], v[236:239], v[36:39]
	ds_read_b128 v[220:223], v203 offset:8192
	s_waitcnt lgkmcnt(4)
	v_mfma_f32_16x16x32_bf16 v[44:47], v[108:111], v[240:243], v[44:47]
	v_mfma_f32_16x16x32_bf16 v[36:39], v[144:147], v[240:243], v[36:39]
	ds_read_b128 v[228:231], v204 offset:8192
	s_waitcnt lgkmcnt(4)
	v_mfma_f32_16x16x32_bf16 v[44:47], v[100:103], v[244:247], v[44:47]
	v_mfma_f32_16x16x32_bf16 v[36:39], v[140:143], v[244:247], v[36:39]
	ds_read_b128 v[232:235], v184 offset:8192
	s_waitcnt lgkmcnt(4)
	v_mfma_f32_16x16x32_bf16 v[44:47], v[92:95], v[212:215], v[44:47]
	v_mfma_f32_16x16x32_bf16 v[36:39], v[132:135], v[212:215], v[36:39]
	ds_read_b128 v[236:239], v184 offset:8256
	s_waitcnt lgkmcnt(4)
	v_mfma_f32_16x16x32_bf16 v[44:47], v[84:87], v[216:219], v[44:47]
	v_mfma_f32_16x16x32_bf16 v[36:39], v[128:131], v[216:219], v[36:39]
	ds_read_b128 v[240:243], v184 offset:8320
	s_waitcnt lgkmcnt(4)
	v_mfma_f32_16x16x32_bf16 v[44:47], v[80:83], v[220:223], v[44:47]
	v_mfma_f32_16x16x32_bf16 v[36:39], v[124:127], v[220:223], v[36:39]
	ds_read_b128 v[244:247], v184 offset:8384
	s_waitcnt lgkmcnt(4)
	v_mfma_f32_16x16x32_bf16 v[44:47], v[76:79], v[228:231], v[44:47]
	v_mfma_f32_16x16x32_bf16 v[36:39], v[116:119], v[228:231], v[36:39]
	ds_read_b128 v[212:215], v197 offset:16384
	s_waitcnt lgkmcnt(4)
	v_mfma_f32_16x16x32_bf16 v[44:47], v[72:75], v[232:235], v[44:47]
	v_mfma_f32_16x16x32_bf16 v[36:39], v[112:115], v[232:235], v[36:39]
	ds_read_b128 v[216:219], v198 offset:16384
	s_waitcnt lgkmcnt(4)
	v_mfma_f32_16x16x32_bf16 v[44:47], v[68:71], v[236:239], v[44:47]
	v_mfma_f32_16x16x32_bf16 v[36:39], v[104:107], v[236:239], v[36:39]
	ds_read_b128 v[220:223], v199 offset:16384
	s_waitcnt lgkmcnt(4)
	v_mfma_f32_16x16x32_bf16 v[44:47], v[64:67], v[240:243], v[44:47]
	v_mfma_f32_16x16x32_bf16 v[36:39], v[96:99], v[240:243], v[36:39]
	ds_read_b128 v[228:231], v200 offset:16384
	s_waitcnt lgkmcnt(4)
	v_mfma_f32_16x16x32_bf16 v[172:175], v[40:43], v[244:247], v[44:47]
	v_mfma_f32_16x16x32_bf16 v[48:51], v[88:91], v[244:247], v[36:39]
	s_nop 3
	ds_read_b128 v[232:235], v201 offset:16384
	s_waitcnt lgkmcnt(4)
	v_mfma_f32_16x16x32_bf16 v[44:47], v[136:139], v[212:215], 0
	v_mfma_f32_16x16x32_bf16 v[36:39], v[152:155], v[212:215], 0
	ds_read_b128 v[236:239], v202 offset:16384
	s_waitcnt lgkmcnt(4)
	v_mfma_f32_16x16x32_bf16 v[44:47], v[120:123], v[216:219], v[44:47]
	v_mfma_f32_16x16x32_bf16 v[36:39], v[148:151], v[216:219], v[36:39]
	ds_read_b128 v[240:243], v203 offset:16384
	s_waitcnt lgkmcnt(4)
	v_mfma_f32_16x16x32_bf16 v[44:47], v[108:111], v[220:223], v[44:47]
	v_mfma_f32_16x16x32_bf16 v[36:39], v[144:147], v[220:223], v[36:39]
	ds_read_b128 v[244:247], v204 offset:16384
	s_waitcnt lgkmcnt(4)
	v_mfma_f32_16x16x32_bf16 v[44:47], v[100:103], v[228:231], v[44:47]
	v_mfma_f32_16x16x32_bf16 v[36:39], v[140:143], v[228:231], v[36:39]
	ds_read_b128 v[212:215], v184 offset:16384
	s_waitcnt lgkmcnt(4)
	v_mfma_f32_16x16x32_bf16 v[44:47], v[92:95], v[232:235], v[44:47]
	v_mfma_f32_16x16x32_bf16 v[36:39], v[132:135], v[232:235], v[36:39]
	ds_read_b128 v[216:219], v184 offset:16448
	s_waitcnt lgkmcnt(4)
	v_mfma_f32_16x16x32_bf16 v[44:47], v[84:87], v[236:239], v[44:47]
	v_mfma_f32_16x16x32_bf16 v[36:39], v[128:131], v[236:239], v[36:39]
	ds_read_b128 v[220:223], v184 offset:16512
	s_waitcnt lgkmcnt(4)
	v_mfma_f32_16x16x32_bf16 v[44:47], v[80:83], v[240:243], v[44:47]
	v_mfma_f32_16x16x32_bf16 v[36:39], v[124:127], v[240:243], v[36:39]
	ds_read_b128 v[228:231], v184 offset:16576
	s_waitcnt lgkmcnt(4)
	v_mfma_f32_16x16x32_bf16 v[44:47], v[76:79], v[244:247], v[44:47]
	v_mfma_f32_16x16x32_bf16 v[36:39], v[116:119], v[244:247], v[36:39]
	ds_read_b128 v[232:235], v197 offset:24576
	s_waitcnt lgkmcnt(4)
	v_mfma_f32_16x16x32_bf16 v[44:47], v[72:75], v[212:215], v[44:47]
	v_mfma_f32_16x16x32_bf16 v[36:39], v[112:115], v[212:215], v[36:39]
	ds_read_b128 v[236:239], v198 offset:24576
	s_waitcnt lgkmcnt(4)
	v_mfma_f32_16x16x32_bf16 v[44:47], v[68:71], v[216:219], v[44:47]
	v_mfma_f32_16x16x32_bf16 v[36:39], v[104:107], v[216:219], v[36:39]
	ds_read_b128 v[240:243], v199 offset:24576
	s_waitcnt lgkmcnt(4)
	v_mfma_f32_16x16x32_bf16 v[44:47], v[64:67], v[220:223], v[44:47]
	v_mfma_f32_16x16x32_bf16 v[36:39], v[96:99], v[220:223], v[36:39]
	ds_read_b128 v[244:247], v200 offset:24576
	s_waitcnt lgkmcnt(4)
	v_mfma_f32_16x16x32_bf16 v[160:163], v[40:43], v[228:231], v[44:47]
	s_nop 3
	v_mfma_f32_16x16x32_bf16 v[36:39], v[88:91], v[228:231], v[36:39]
	ds_read_b128 v[212:215], v201 offset:24576
	s_waitcnt lgkmcnt(4)
	v_mfma_f32_16x16x32_bf16 v[52:55], v[136:139], v[232:235], 0
	v_mfma_f32_16x16x32_bf16 v[44:47], v[152:155], v[232:235], 0
	ds_read_b128 v[216:219], v202 offset:24576
	s_waitcnt lgkmcnt(4)
	v_mfma_f32_16x16x32_bf16 v[52:55], v[120:123], v[236:239], v[52:55]
	v_mfma_f32_16x16x32_bf16 v[44:47], v[148:151], v[236:239], v[44:47]
	ds_read_b128 v[220:223], v203 offset:24576
	s_waitcnt lgkmcnt(4)
	v_mfma_f32_16x16x32_bf16 v[52:55], v[108:111], v[240:243], v[52:55]
	v_mfma_f32_16x16x32_bf16 v[44:47], v[144:147], v[240:243], v[44:47]
	ds_read_b128 v[228:231], v204 offset:24576
	s_waitcnt lgkmcnt(4)
	v_mfma_f32_16x16x32_bf16 v[52:55], v[100:103], v[244:247], v[52:55]
	v_mfma_f32_16x16x32_bf16 v[44:47], v[140:143], v[244:247], v[44:47]
	ds_read_b128 v[232:235], v184 offset:24576
	s_waitcnt lgkmcnt(4)
	v_mfma_f32_16x16x32_bf16 v[52:55], v[92:95], v[212:215], v[52:55]
	v_mfma_f32_16x16x32_bf16 v[44:47], v[132:135], v[212:215], v[44:47]
	ds_read_b128 v[236:239], v184 offset:24640
	s_waitcnt lgkmcnt(4)
	v_mfma_f32_16x16x32_bf16 v[52:55], v[84:87], v[216:219], v[52:55]
	v_mfma_f32_16x16x32_bf16 v[44:47], v[128:131], v[216:219], v[44:47]
	ds_read_b128 v[240:243], v184 offset:24704
	s_waitcnt lgkmcnt(4)
	v_mfma_f32_16x16x32_bf16 v[52:55], v[80:83], v[220:223], v[52:55]
	v_mfma_f32_16x16x32_bf16 v[44:47], v[124:127], v[220:223], v[44:47]
	ds_read_b128 v[244:247], v184 offset:24768
	s_waitcnt lgkmcnt(4)
	v_mfma_f32_16x16x32_bf16 v[52:55], v[76:79], v[228:231], v[52:55]
	v_mfma_f32_16x16x32_bf16 v[44:47], v[116:119], v[228:231], v[44:47]
	ds_read_b128 v[212:215], v197 offset:32768
	s_waitcnt lgkmcnt(4)
	v_mfma_f32_16x16x32_bf16 v[52:55], v[72:75], v[232:235], v[52:55]
	v_mfma_f32_16x16x32_bf16 v[44:47], v[112:115], v[232:235], v[44:47]
	ds_read_b128 v[216:219], v198 offset:32768
	s_waitcnt lgkmcnt(4)
	v_mfma_f32_16x16x32_bf16 v[52:55], v[68:71], v[236:239], v[52:55]
	v_mfma_f32_16x16x32_bf16 v[44:47], v[104:107], v[236:239], v[44:47]
	ds_read_b128 v[220:223], v199 offset:32768
	s_waitcnt lgkmcnt(4)
	v_mfma_f32_16x16x32_bf16 v[52:55], v[64:67], v[240:243], v[52:55]
	v_mfma_f32_16x16x32_bf16 v[44:47], v[96:99], v[240:243], v[44:47]
	ds_read_b128 v[228:231], v200 offset:32768
	s_waitcnt lgkmcnt(4)
	v_mfma_f32_16x16x32_bf16 v[60:63], v[88:91], v[244:247], v[44:47]
	s_nop 4
	v_mfma_f32_16x16x32_bf16 v[180:183], v[40:43], v[244:247], v[52:55]
	ds_read_b128 v[232:235], v201 offset:32768
	s_waitcnt lgkmcnt(4)
	v_mfma_f32_16x16x32_bf16 v[52:55], v[136:139], v[212:215], 0
	v_mfma_f32_16x16x32_bf16 v[44:47], v[152:155], v[212:215], 0
	ds_read_b128 v[236:239], v202 offset:32768
	s_waitcnt lgkmcnt(4)
	v_mfma_f32_16x16x32_bf16 v[52:55], v[120:123], v[216:219], v[52:55]
	v_mfma_f32_16x16x32_bf16 v[44:47], v[148:151], v[216:219], v[44:47]
	ds_read_b128 v[240:243], v203 offset:32768
	s_waitcnt lgkmcnt(4)
	v_mfma_f32_16x16x32_bf16 v[52:55], v[108:111], v[220:223], v[52:55]
	v_mfma_f32_16x16x32_bf16 v[44:47], v[144:147], v[220:223], v[44:47]
	ds_read_b128 v[244:247], v204 offset:32768
	s_waitcnt lgkmcnt(4)
	v_mfma_f32_16x16x32_bf16 v[52:55], v[100:103], v[228:231], v[52:55]
	v_mfma_f32_16x16x32_bf16 v[44:47], v[140:143], v[228:231], v[44:47]
	ds_read_b128 v[212:215], v184 offset:32768
	s_waitcnt lgkmcnt(4)
	v_mfma_f32_16x16x32_bf16 v[52:55], v[92:95], v[232:235], v[52:55]
	v_mfma_f32_16x16x32_bf16 v[44:47], v[132:135], v[232:235], v[44:47]
	ds_read_b128 v[216:219], v184 offset:32832
	s_waitcnt lgkmcnt(4)
	v_mfma_f32_16x16x32_bf16 v[52:55], v[84:87], v[236:239], v[52:55]
	v_mfma_f32_16x16x32_bf16 v[44:47], v[128:131], v[236:239], v[44:47]
	ds_read_b128 v[220:223], v184 offset:32896
	s_waitcnt lgkmcnt(4)
	v_mfma_f32_16x16x32_bf16 v[52:55], v[80:83], v[240:243], v[52:55]
	v_mfma_f32_16x16x32_bf16 v[44:47], v[124:127], v[240:243], v[44:47]
	ds_read_b128 v[228:231], v184 offset:32960
	s_waitcnt lgkmcnt(4)
	v_mfma_f32_16x16x32_bf16 v[52:55], v[76:79], v[244:247], v[52:55]
	v_mfma_f32_16x16x32_bf16 v[44:47], v[116:119], v[244:247], v[44:47]
	ds_read_b128 v[232:235], v197 offset:40960
	s_waitcnt lgkmcnt(4)
	v_mfma_f32_16x16x32_bf16 v[52:55], v[72:75], v[212:215], v[52:55]
	v_mfma_f32_16x16x32_bf16 v[44:47], v[112:115], v[212:215], v[44:47]
	ds_read_b128 v[236:239], v198 offset:40960
	s_waitcnt lgkmcnt(4)
	v_mfma_f32_16x16x32_bf16 v[52:55], v[68:71], v[216:219], v[52:55]
	v_mfma_f32_16x16x32_bf16 v[44:47], v[104:107], v[216:219], v[44:47]
	ds_read_b128 v[240:243], v199 offset:40960
	s_waitcnt lgkmcnt(4)
	v_mfma_f32_16x16x32_bf16 v[52:55], v[64:67], v[220:223], v[52:55]
	v_mfma_f32_16x16x32_bf16 v[44:47], v[96:99], v[220:223], v[44:47]
	ds_read_b128 v[244:247], v200 offset:40960
	s_waitcnt lgkmcnt(4)
	v_mfma_f32_16x16x32_bf16 v[168:171], v[40:43], v[228:231], v[52:55]
	v_mfma_f32_16x16x32_bf16 v[52:55], v[88:91], v[228:231], v[44:47]
	s_nop 3
	ds_read_b128 v[212:215], v201 offset:40960
	s_waitcnt lgkmcnt(4)
	v_mfma_f32_16x16x32_bf16 v[56:59], v[136:139], v[232:235], 0
	v_mfma_f32_16x16x32_bf16 v[44:47], v[152:155], v[232:235], 0
	ds_read_b128 v[216:219], v202 offset:40960
	s_waitcnt lgkmcnt(4)
	v_mfma_f32_16x16x32_bf16 v[56:59], v[120:123], v[236:239], v[56:59]
	v_mfma_f32_16x16x32_bf16 v[44:47], v[148:151], v[236:239], v[44:47]
	ds_read_b128 v[220:223], v203 offset:40960
	s_waitcnt lgkmcnt(4)
	v_mfma_f32_16x16x32_bf16 v[56:59], v[108:111], v[240:243], v[56:59]
	v_mfma_f32_16x16x32_bf16 v[44:47], v[144:147], v[240:243], v[44:47]
	ds_read_b128 v[228:231], v204 offset:40960
	s_waitcnt lgkmcnt(4)
	v_mfma_f32_16x16x32_bf16 v[56:59], v[100:103], v[244:247], v[56:59]
	v_mfma_f32_16x16x32_bf16 v[44:47], v[140:143], v[244:247], v[44:47]
	ds_read_b128 v[232:235], v184 offset:40960
	s_waitcnt lgkmcnt(4)
	v_mfma_f32_16x16x32_bf16 v[56:59], v[92:95], v[212:215], v[56:59]
	v_mfma_f32_16x16x32_bf16 v[44:47], v[132:135], v[212:215], v[44:47]
	ds_read_b128 v[236:239], v184 offset:41024
	s_waitcnt lgkmcnt(4)
	v_mfma_f32_16x16x32_bf16 v[56:59], v[84:87], v[216:219], v[56:59]
	v_mfma_f32_16x16x32_bf16 v[44:47], v[128:131], v[216:219], v[44:47]
	ds_read_b128 v[240:243], v184 offset:41088
	s_waitcnt lgkmcnt(4)
	v_mfma_f32_16x16x32_bf16 v[56:59], v[80:83], v[220:223], v[56:59]
	v_mfma_f32_16x16x32_bf16 v[44:47], v[124:127], v[220:223], v[44:47]
	ds_read_b128 v[244:247], v184 offset:41152
	s_waitcnt lgkmcnt(4)
	v_mfma_f32_16x16x32_bf16 v[56:59], v[76:79], v[228:231], v[56:59]
	v_mfma_f32_16x16x32_bf16 v[44:47], v[116:119], v[228:231], v[44:47]
	ds_read_b128 v[212:215], v197 offset:49152
	s_waitcnt lgkmcnt(4)
	v_mfma_f32_16x16x32_bf16 v[56:59], v[72:75], v[232:235], v[56:59]
	v_mfma_f32_16x16x32_bf16 v[44:47], v[112:115], v[232:235], v[44:47]
	ds_read_b128 v[216:219], v198 offset:49152
	s_waitcnt lgkmcnt(4)
	v_mfma_f32_16x16x32_bf16 v[56:59], v[68:71], v[236:239], v[56:59]
	v_mfma_f32_16x16x32_bf16 v[44:47], v[104:107], v[236:239], v[44:47]
	ds_read_b128 v[220:223], v199 offset:49152
	s_waitcnt lgkmcnt(4)
	v_mfma_f32_16x16x32_bf16 v[56:59], v[64:67], v[240:243], v[56:59]
	v_mfma_f32_16x16x32_bf16 v[44:47], v[96:99], v[240:243], v[44:47]
	ds_read_b128 v[228:231], v200 offset:49152
	s_waitcnt lgkmcnt(4)
	v_mfma_f32_16x16x32_bf16 v[176:179], v[40:43], v[244:247], v[56:59]
	v_mfma_f32_16x16x32_bf16 v[56:59], v[88:91], v[244:247], v[44:47]
	s_nop 3
	ds_read_b128 v[232:235], v201 offset:49152
	s_waitcnt lgkmcnt(4)
	v_mfma_f32_16x16x32_bf16 v[164:167], v[136:139], v[212:215], 0
	v_mfma_f32_16x16x32_bf16 v[44:47], v[152:155], v[212:215], 0
	ds_read_b128 v[236:239], v202 offset:49152
	s_waitcnt lgkmcnt(4)
	v_mfma_f32_16x16x32_bf16 v[164:167], v[120:123], v[216:219], v[164:167]
	v_mfma_f32_16x16x32_bf16 v[44:47], v[148:151], v[216:219], v[44:47]
	ds_read_b128 v[240:243], v203 offset:49152
	s_waitcnt lgkmcnt(4)
	v_mfma_f32_16x16x32_bf16 v[164:167], v[108:111], v[220:223], v[164:167]
	v_mfma_f32_16x16x32_bf16 v[44:47], v[144:147], v[220:223], v[44:47]
	ds_read_b128 v[244:247], v204 offset:49152
	s_waitcnt lgkmcnt(4)
	v_mfma_f32_16x16x32_bf16 v[164:167], v[100:103], v[228:231], v[164:167]
	v_mfma_f32_16x16x32_bf16 v[44:47], v[140:143], v[228:231], v[44:47]
	ds_read_b128 v[212:215], v184 offset:49152
	s_waitcnt lgkmcnt(4)
	v_mfma_f32_16x16x32_bf16 v[164:167], v[92:95], v[232:235], v[164:167]
	v_mfma_f32_16x16x32_bf16 v[44:47], v[132:135], v[232:235], v[44:47]
	ds_read_b128 v[216:219], v184 offset:49216
	s_waitcnt lgkmcnt(4)
	v_mfma_f32_16x16x32_bf16 v[164:167], v[84:87], v[236:239], v[164:167]
	v_mfma_f32_16x16x32_bf16 v[44:47], v[128:131], v[236:239], v[44:47]
	ds_read_b128 v[220:223], v184 offset:49280
	s_waitcnt lgkmcnt(4)
	v_mfma_f32_16x16x32_bf16 v[164:167], v[80:83], v[240:243], v[164:167]
	v_mfma_f32_16x16x32_bf16 v[44:47], v[124:127], v[240:243], v[44:47]
	ds_read_b128 v[228:231], v184 offset:49344
	s_waitcnt lgkmcnt(4)
	v_mfma_f32_16x16x32_bf16 v[164:167], v[76:79], v[244:247], v[164:167]
	v_mfma_f32_16x16x32_bf16 v[44:47], v[116:119], v[244:247], v[44:47]
	ds_read_b128 v[232:235], v197 offset:57344
	s_waitcnt lgkmcnt(4)
	v_mfma_f32_16x16x32_bf16 v[164:167], v[72:75], v[212:215], v[164:167]
	v_mfma_f32_16x16x32_bf16 v[44:47], v[112:115], v[212:215], v[44:47]
	ds_read_b128 v[236:239], v198 offset:57344
	s_waitcnt lgkmcnt(4)
	v_mfma_f32_16x16x32_bf16 v[164:167], v[68:71], v[216:219], v[164:167]
	v_mfma_f32_16x16x32_bf16 v[44:47], v[104:107], v[216:219], v[44:47]
	ds_read_b128 v[240:243], v199 offset:57344
	s_waitcnt lgkmcnt(4)
	v_mfma_f32_16x16x32_bf16 v[164:167], v[64:67], v[220:223], v[164:167]
	v_mfma_f32_16x16x32_bf16 v[44:47], v[96:99], v[220:223], v[44:47]
	ds_read_b128 v[244:247], v200 offset:57344
	s_waitcnt lgkmcnt(4)
	v_mfma_f32_16x16x32_bf16 v[164:167], v[40:43], v[228:231], v[164:167]
	v_mfma_f32_16x16x32_bf16 v[44:47], v[88:91], v[228:231], v[44:47]
	ds_read_b128 v[212:215], v201 offset:57344
	s_waitcnt lgkmcnt(4)
	v_mfma_f32_16x16x32_bf16 v[136:139], v[136:139], v[232:235], 0
	v_mfma_f32_16x16x32_bf16 v[152:155], v[152:155], v[232:235], 0
	ds_read_b128 v[216:219], v202 offset:57344
	s_waitcnt lgkmcnt(4)
	v_mfma_f32_16x16x32_bf16 v[120:123], v[120:123], v[236:239], v[136:139]
	v_mfma_f32_16x16x32_bf16 v[136:139], v[148:151], v[236:239], v[152:155]
	ds_read_b128 v[220:223], v203 offset:57344
	s_waitcnt lgkmcnt(4)
	v_mfma_f32_16x16x32_bf16 v[108:111], v[108:111], v[240:243], v[120:123]
	v_mfma_f32_16x16x32_bf16 v[120:123], v[144:147], v[240:243], v[136:139]
	s_nop 3
	ds_read_b128 v[228:231], v204 offset:57344
	s_waitcnt lgkmcnt(4)
	v_mfma_f32_16x16x32_bf16 v[100:103], v[100:103], v[244:247], v[108:111]
	v_mfma_f32_16x16x32_bf16 v[108:111], v[140:143], v[244:247], v[120:123]
	s_nop 2
	ds_read_b128 v[232:235], v184 offset:57344
	s_waitcnt lgkmcnt(4)
	v_mfma_f32_16x16x32_bf16 v[92:95], v[92:95], v[212:215], v[100:103]
	v_mfma_f32_16x16x32_bf16 v[100:103], v[132:135], v[212:215], v[108:111]
	s_nop 2
	ds_read_b128 v[236:239], v184 offset:57408
	s_waitcnt lgkmcnt(4)
	v_mfma_f32_16x16x32_bf16 v[84:87], v[84:87], v[216:219], v[92:95]
	v_mfma_f32_16x16x32_bf16 v[92:95], v[128:131], v[216:219], v[100:103]
	s_nop 2
	ds_read_b128 v[240:243], v184 offset:57472
	s_waitcnt lgkmcnt(4)
	v_mfma_f32_16x16x32_bf16 v[80:83], v[80:83], v[220:223], v[84:87]
	v_mfma_f32_16x16x32_bf16 v[84:87], v[124:127], v[220:223], v[92:95]
	s_nop 2
	ds_read_b128 v[244:247], v184 offset:57536
	s_waitcnt lgkmcnt(4)
	v_mfma_f32_16x16x32_bf16 v[76:79], v[76:79], v[228:231], v[80:83]
	v_mfma_f32_16x16x32_bf16 v[80:83], v[116:119], v[228:231], v[84:87]
	s_nop 2
	s_waitcnt lgkmcnt(3)
	v_mfma_f32_16x16x32_bf16 v[72:75], v[72:75], v[232:235], v[76:79]
	v_mfma_f32_16x16x32_bf16 v[76:79], v[112:115], v[232:235], v[80:83]
	s_nop 2
	s_waitcnt lgkmcnt(2)
	v_mfma_f32_16x16x32_bf16 v[68:71], v[68:71], v[236:239], v[72:75]
	v_mfma_f32_16x16x32_bf16 v[72:75], v[104:107], v[236:239], v[76:79]
	s_nop 2
	s_waitcnt lgkmcnt(1)
	v_mfma_f32_16x16x32_bf16 v[64:67], v[64:67], v[240:243], v[68:71]
	v_mfma_f32_16x16x32_bf16 v[68:71], v[96:99], v[240:243], v[72:75]
	s_nop 2
	s_waitcnt lgkmcnt(0)
	v_mfma_f32_16x16x32_bf16 v[64:67], v[40:43], v[244:247], v[64:67]
	s_barrier
	v_mfma_f32_16x16x32_bf16 v[40:43], v[88:91], v[244:247], v[68:71]
	s_nop 2
	v_mov_b32_e32 v80, 0xbdd2d3e8
	v_mov_b32_e32 v81, 0xbdd2d3e8
	v_mov_b32_e32 v82, 0xc0135761
	v_mov_b32_e32 v83, 0xc0135761
	v_mov_b32_e32 v84, 1.0
	v_mov_b32_e32 v85, 1.0
	v_pk_mul_f32 v[76:77], v[156:157], v[156:157]
	v_pk_mul_f32 v[78:79], v[158:159], v[158:159]
	v_pk_fma_f32 v[76:77], v[76:77], v[80:81], v[82:83]
	v_pk_fma_f32 v[78:79], v[78:79], v[80:81], v[82:83]
	v_pk_mul_f32 v[76:77], v[156:157], v[76:77]
	v_pk_mul_f32 v[78:79], v[158:159], v[78:79]
	v_exp_f32_e32 v76, v76
	v_exp_f32_e32 v77, v77
	v_exp_f32_e32 v78, v78
	v_exp_f32_e32 v79, v79
	v_pk_add_f32 v[76:77], v[76:77], v[84:85]
	v_pk_add_f32 v[78:79], v[78:79], v[84:85]
	v_rcp_f32_e32 v76, v76
	v_rcp_f32_e32 v77, v77
	v_rcp_f32_e32 v78, v78
	v_rcp_f32_e32 v79, v79
	v_pk_mul_f32 v[76:77], v[156:157], v[76:77]
	v_pk_mul_f32 v[78:79], v[158:159], v[78:79]
	v_cvt_pk_bf16_f32 v70, v76, v77
	v_cvt_pk_bf16_f32 v71, v78, v79
	v_add_u32_e32 v68, s50, v196
	v_add3_u32 v68, 0, v205, v68
	v_mbcnt_lo_u32_b32 v94, -1, 0
	v_mbcnt_hi_u32_b32 v94, -1, v94
	v_and_b32_e32 v94, 7, v94
	v_lshlrev_b32_e32 v94, 4, v94
	v_or_b32_e32 v95, 32, v68
	v_xor_b32_e32 v68, v94, v68
	v_xor_b32_e32 v95, v94, v95
	ds_write_b64 v68, v[70:71]
	v_pk_mul_f32 v[86:87], v[172:173], v[172:173]
	v_pk_mul_f32 v[92:93], v[174:175], v[174:175]
	v_pk_fma_f32 v[86:87], v[86:87], v[80:81], v[82:83]
	v_pk_fma_f32 v[92:93], v[92:93], v[80:81], v[82:83]
	v_pk_mul_f32 v[86:87], v[172:173], v[86:87]
	v_pk_mul_f32 v[92:93], v[174:175], v[92:93]
	v_exp_f32_e32 v86, v86
	v_exp_f32_e32 v87, v87
	v_exp_f32_e32 v92, v92
	v_exp_f32_e32 v93, v93
	v_pk_add_f32 v[86:87], v[86:87], v[84:85]
	v_pk_add_f32 v[92:93], v[92:93], v[84:85]
	v_rcp_f32_e32 v86, v86
	v_rcp_f32_e32 v87, v87
	v_rcp_f32_e32 v92, v92
	v_rcp_f32_e32 v93, v93
	v_pk_mul_f32 v[86:87], v[172:173], v[86:87]
	v_pk_mul_f32 v[92:93], v[174:175], v[92:93]
	v_cvt_pk_bf16_f32 v70, v86, v87
	v_cvt_pk_bf16_f32 v71, v92, v93
	ds_write_b64 v68, v[70:71] offset:8192
	v_pk_mul_f32 v[76:77], v[160:161], v[160:161]
	v_pk_mul_f32 v[78:79], v[162:163], v[162:163]
	v_pk_fma_f32 v[76:77], v[76:77], v[80:81], v[82:83]
	v_pk_fma_f32 v[78:79], v[78:79], v[80:81], v[82:83]
	v_pk_mul_f32 v[76:77], v[160:161], v[76:77]
	v_pk_mul_f32 v[78:79], v[162:163], v[78:79]
	v_exp_f32_e32 v76, v76
	v_exp_f32_e32 v77, v77
	v_exp_f32_e32 v78, v78
	v_exp_f32_e32 v79, v79
	v_pk_add_f32 v[76:77], v[76:77], v[84:85]
	v_pk_add_f32 v[78:79], v[78:79], v[84:85]
	v_rcp_f32_e32 v76, v76
	v_rcp_f32_e32 v77, v77
	v_rcp_f32_e32 v78, v78
	v_rcp_f32_e32 v79, v79
	v_pk_mul_f32 v[76:77], v[160:161], v[76:77]
	v_pk_mul_f32 v[78:79], v[162:163], v[78:79]
	v_cvt_pk_bf16_f32 v70, v76, v77
	v_cvt_pk_bf16_f32 v71, v78, v79
	ds_write_b64 v68, v[70:71] offset:16384
	v_pk_mul_f32 v[86:87], v[180:181], v[180:181]
	v_pk_mul_f32 v[92:93], v[182:183], v[182:183]
	v_pk_fma_f32 v[86:87], v[86:87], v[80:81], v[82:83]
	v_pk_fma_f32 v[92:93], v[92:93], v[80:81], v[82:83]
	v_pk_mul_f32 v[86:87], v[180:181], v[86:87]
	v_pk_mul_f32 v[92:93], v[182:183], v[92:93]
	v_exp_f32_e32 v86, v86
	v_exp_f32_e32 v87, v87
	v_exp_f32_e32 v92, v92
	v_exp_f32_e32 v93, v93
	v_pk_add_f32 v[86:87], v[86:87], v[84:85]
	v_pk_add_f32 v[92:93], v[92:93], v[84:85]
	v_rcp_f32_e32 v86, v86
	v_rcp_f32_e32 v87, v87
	v_rcp_f32_e32 v92, v92
	v_rcp_f32_e32 v93, v93
	v_pk_mul_f32 v[86:87], v[180:181], v[86:87]
	v_pk_mul_f32 v[92:93], v[182:183], v[92:93]
	v_cvt_pk_bf16_f32 v70, v86, v87
	v_cvt_pk_bf16_f32 v71, v92, v93
	ds_write_b64 v68, v[70:71] offset:24576
	v_pk_mul_f32 v[76:77], v[168:169], v[168:169]
	v_pk_mul_f32 v[78:79], v[170:171], v[170:171]
	v_pk_fma_f32 v[76:77], v[76:77], v[80:81], v[82:83]
	v_pk_fma_f32 v[78:79], v[78:79], v[80:81], v[82:83]
	v_pk_mul_f32 v[76:77], v[168:169], v[76:77]
	v_pk_mul_f32 v[78:79], v[170:171], v[78:79]
	v_exp_f32_e32 v76, v76
	v_exp_f32_e32 v77, v77
	v_exp_f32_e32 v78, v78
	v_exp_f32_e32 v79, v79
	v_pk_add_f32 v[76:77], v[76:77], v[84:85]
	v_pk_add_f32 v[78:79], v[78:79], v[84:85]
	v_rcp_f32_e32 v76, v76
	v_rcp_f32_e32 v77, v77
	v_rcp_f32_e32 v78, v78
	v_rcp_f32_e32 v79, v79
	v_pk_mul_f32 v[76:77], v[168:169], v[76:77]
	v_pk_mul_f32 v[78:79], v[170:171], v[78:79]
	v_cvt_pk_bf16_f32 v70, v76, v77
	v_cvt_pk_bf16_f32 v71, v78, v79
	ds_write_b64 v68, v[70:71] offset:32768
	v_pk_mul_f32 v[86:87], v[176:177], v[176:177]
	v_pk_mul_f32 v[92:93], v[178:179], v[178:179]
	v_pk_fma_f32 v[86:87], v[86:87], v[80:81], v[82:83]
	v_pk_fma_f32 v[92:93], v[92:93], v[80:81], v[82:83]
	v_pk_mul_f32 v[86:87], v[176:177], v[86:87]
	v_pk_mul_f32 v[92:93], v[178:179], v[92:93]
	v_exp_f32_e32 v86, v86
	v_exp_f32_e32 v87, v87
	v_exp_f32_e32 v92, v92
	v_exp_f32_e32 v93, v93
	v_pk_add_f32 v[86:87], v[86:87], v[84:85]
	v_pk_add_f32 v[92:93], v[92:93], v[84:85]
	v_rcp_f32_e32 v86, v86
	v_rcp_f32_e32 v87, v87
	v_rcp_f32_e32 v92, v92
	v_rcp_f32_e32 v93, v93
	v_pk_mul_f32 v[86:87], v[176:177], v[86:87]
	v_pk_mul_f32 v[92:93], v[178:179], v[92:93]
	v_cvt_pk_bf16_f32 v70, v86, v87
	v_cvt_pk_bf16_f32 v71, v92, v93
	ds_write_b64 v68, v[70:71] offset:40960
	v_pk_mul_f32 v[76:77], v[164:165], v[164:165]
	v_pk_mul_f32 v[78:79], v[166:167], v[166:167]
	v_pk_fma_f32 v[76:77], v[76:77], v[80:81], v[82:83]
	v_pk_fma_f32 v[78:79], v[78:79], v[80:81], v[82:83]
	v_pk_mul_f32 v[76:77], v[164:165], v[76:77]
	v_pk_mul_f32 v[78:79], v[166:167], v[78:79]
	v_exp_f32_e32 v76, v76
	v_exp_f32_e32 v77, v77
	v_exp_f32_e32 v78, v78
	v_exp_f32_e32 v79, v79
	v_pk_add_f32 v[76:77], v[76:77], v[84:85]
	v_pk_add_f32 v[78:79], v[78:79], v[84:85]
	v_rcp_f32_e32 v76, v76
	v_rcp_f32_e32 v77, v77
	v_rcp_f32_e32 v78, v78
	v_rcp_f32_e32 v79, v79
	v_pk_mul_f32 v[76:77], v[164:165], v[76:77]
	v_pk_mul_f32 v[78:79], v[166:167], v[78:79]
	v_cvt_pk_bf16_f32 v70, v76, v77
	v_cvt_pk_bf16_f32 v71, v78, v79
	ds_write_b64 v68, v[70:71] offset:49152
	s_nop 0
	v_pk_mul_f32 v[86:87], v[64:65], v[64:65]
	v_pk_mul_f32 v[92:93], v[66:67], v[66:67]
	v_pk_fma_f32 v[86:87], v[86:87], v[80:81], v[82:83]
	v_pk_fma_f32 v[92:93], v[92:93], v[80:81], v[82:83]
	v_pk_mul_f32 v[86:87], v[64:65], v[86:87]
	v_pk_mul_f32 v[92:93], v[66:67], v[92:93]
	v_exp_f32_e32 v86, v86
	v_exp_f32_e32 v87, v87
	v_exp_f32_e32 v92, v92
	v_exp_f32_e32 v93, v93
	v_pk_add_f32 v[86:87], v[86:87], v[84:85]
	v_pk_add_f32 v[92:93], v[92:93], v[84:85]
	v_rcp_f32_e32 v86, v86
	v_rcp_f32_e32 v87, v87
	v_rcp_f32_e32 v92, v92
	v_rcp_f32_e32 v93, v93
	v_pk_mul_f32 v[86:87], v[64:65], v[86:87]
	v_pk_mul_f32 v[92:93], v[66:67], v[92:93]
	s_nop 0
	s_nop 0
	v_cvt_pk_bf16_f32 v64, v86, v87
	s_nop 0
	s_nop 0
	s_nop 0
	s_nop 0
	v_cvt_pk_bf16_f32 v65, v92, v93
	ds_write_b64 v68, v[64:65] offset:57344
	s_nop 0
	s_nop 0
	v_pk_mul_f32 v[76:77], v[32:33], v[32:33]
	v_pk_mul_f32 v[78:79], v[34:35], v[34:35]
	v_pk_fma_f32 v[76:77], v[76:77], v[80:81], v[82:83]
	v_pk_fma_f32 v[78:79], v[78:79], v[80:81], v[82:83]
	v_pk_mul_f32 v[76:77], v[32:33], v[76:77]
	v_pk_mul_f32 v[78:79], v[34:35], v[78:79]
	v_exp_f32_e32 v76, v76
	v_exp_f32_e32 v77, v77
	v_exp_f32_e32 v78, v78
	v_exp_f32_e32 v79, v79
	v_pk_add_f32 v[76:77], v[76:77], v[84:85]
	v_pk_add_f32 v[78:79], v[78:79], v[84:85]
	v_rcp_f32_e32 v76, v76
	v_rcp_f32_e32 v77, v77
	v_rcp_f32_e32 v78, v78
	v_rcp_f32_e32 v79, v79
	v_pk_mul_f32 v[76:77], v[32:33], v[76:77]
	v_pk_mul_f32 v[78:79], v[34:35], v[78:79]
	s_nop 0
	s_nop 0
	v_cvt_pk_bf16_f32 v32, v76, v77
	s_nop 0
	s_nop 0
	s_nop 0
	s_nop 0
	v_cvt_pk_bf16_f32 v33, v78, v79
	ds_write_b64 v95, v[32:33]
	v_pk_mul_f32 v[86:87], v[48:49], v[48:49]
	v_pk_mul_f32 v[92:93], v[50:51], v[50:51]
	v_pk_fma_f32 v[86:87], v[86:87], v[80:81], v[82:83]
	v_pk_fma_f32 v[92:93], v[92:93], v[80:81], v[82:83]
	v_pk_mul_f32 v[86:87], v[48:49], v[86:87]
	v_pk_mul_f32 v[92:93], v[50:51], v[92:93]
	v_exp_f32_e32 v86, v86
	v_exp_f32_e32 v87, v87
	v_exp_f32_e32 v92, v92
	v_exp_f32_e32 v93, v93
	v_pk_add_f32 v[86:87], v[86:87], v[84:85]
	v_pk_add_f32 v[92:93], v[92:93], v[84:85]
	v_rcp_f32_e32 v86, v86
	v_rcp_f32_e32 v87, v87
	v_rcp_f32_e32 v92, v92
	v_rcp_f32_e32 v93, v93
	v_pk_mul_f32 v[86:87], v[48:49], v[86:87]
	v_pk_mul_f32 v[92:93], v[50:51], v[92:93]
	v_cvt_pk_bf16_f32 v32, v86, v87
	v_cvt_pk_bf16_f32 v33, v92, v93
	ds_write_b64 v95, v[32:33] offset:8192
	v_pk_mul_f32 v[76:77], v[36:37], v[36:37]
	v_pk_mul_f32 v[78:79], v[38:39], v[38:39]
	v_pk_fma_f32 v[76:77], v[76:77], v[80:81], v[82:83]
	v_pk_fma_f32 v[78:79], v[78:79], v[80:81], v[82:83]
	v_pk_mul_f32 v[76:77], v[36:37], v[76:77]
	v_pk_mul_f32 v[78:79], v[38:39], v[78:79]
	v_exp_f32_e32 v76, v76
	v_exp_f32_e32 v77, v77
	v_exp_f32_e32 v78, v78
	v_exp_f32_e32 v79, v79
	v_pk_add_f32 v[76:77], v[76:77], v[84:85]
	v_pk_add_f32 v[78:79], v[78:79], v[84:85]
	v_rcp_f32_e32 v76, v76
	v_rcp_f32_e32 v77, v77
	v_rcp_f32_e32 v78, v78
	v_rcp_f32_e32 v79, v79
	v_pk_mul_f32 v[76:77], v[36:37], v[76:77]
	v_pk_mul_f32 v[78:79], v[38:39], v[78:79]
	v_cvt_pk_bf16_f32 v32, v76, v77
	v_lshl_add_u64 v[36:37], v[186:187], 4, s[22:23]
	v_add_co_u32_e32 v38, vcc, s25, v36
	v_cvt_pk_bf16_f32 v33, v78, v79
	ds_write_b64 v95, v[32:33] offset:16384
	v_pk_mul_f32 v[86:87], v[60:61], v[60:61]
	v_pk_mul_f32 v[92:93], v[62:63], v[62:63]
	v_pk_fma_f32 v[86:87], v[86:87], v[80:81], v[82:83]
	v_pk_fma_f32 v[92:93], v[92:93], v[80:81], v[82:83]
	v_pk_mul_f32 v[86:87], v[60:61], v[86:87]
	v_pk_mul_f32 v[92:93], v[62:63], v[92:93]
	v_exp_f32_e32 v86, v86
	v_exp_f32_e32 v87, v87
	v_exp_f32_e32 v92, v92
	v_exp_f32_e32 v93, v93
	v_pk_add_f32 v[86:87], v[86:87], v[84:85]
	v_pk_add_f32 v[92:93], v[92:93], v[84:85]
	v_rcp_f32_e32 v86, v86
	v_rcp_f32_e32 v87, v87
	v_rcp_f32_e32 v92, v92
	v_rcp_f32_e32 v93, v93
	v_pk_mul_f32 v[86:87], v[60:61], v[86:87]
	v_pk_mul_f32 v[92:93], v[62:63], v[92:93]
	v_cvt_pk_bf16_f32 v32, v86, v87
	v_addc_co_u32_e32 v39, vcc, 0, v37, vcc
	v_cvt_pk_bf16_f32 v33, v92, v93
	ds_write_b64 v95, v[32:33] offset:24576
	v_pk_mul_f32 v[76:77], v[52:53], v[52:53]
	v_pk_mul_f32 v[78:79], v[54:55], v[54:55]
	v_pk_fma_f32 v[76:77], v[76:77], v[80:81], v[82:83]
	v_pk_fma_f32 v[78:79], v[78:79], v[80:81], v[82:83]
	v_pk_mul_f32 v[76:77], v[52:53], v[76:77]
	v_pk_mul_f32 v[78:79], v[54:55], v[78:79]
	v_exp_f32_e32 v76, v76
	v_exp_f32_e32 v77, v77
	v_exp_f32_e32 v78, v78
	v_exp_f32_e32 v79, v79
	v_pk_add_f32 v[76:77], v[76:77], v[84:85]
	v_pk_add_f32 v[78:79], v[78:79], v[84:85]
	v_rcp_f32_e32 v76, v76
	v_rcp_f32_e32 v77, v77
	v_rcp_f32_e32 v78, v78
	v_rcp_f32_e32 v79, v79
	v_pk_mul_f32 v[76:77], v[52:53], v[76:77]
	v_pk_mul_f32 v[78:79], v[54:55], v[78:79]
	v_cvt_pk_bf16_f32 v32, v76, v77
	v_cvt_pk_bf16_f32 v33, v78, v79
	ds_write_b64 v95, v[32:33] offset:32768
	v_pk_mul_f32 v[86:87], v[56:57], v[56:57]
	v_pk_mul_f32 v[92:93], v[58:59], v[58:59]
	v_pk_fma_f32 v[86:87], v[86:87], v[80:81], v[82:83]
	v_pk_fma_f32 v[92:93], v[92:93], v[80:81], v[82:83]
	v_pk_mul_f32 v[86:87], v[56:57], v[86:87]
	v_pk_mul_f32 v[92:93], v[58:59], v[92:93]
	v_exp_f32_e32 v86, v86
	v_exp_f32_e32 v87, v87
	v_exp_f32_e32 v92, v92
	v_exp_f32_e32 v93, v93
	v_pk_add_f32 v[86:87], v[86:87], v[84:85]
	v_pk_add_f32 v[92:93], v[92:93], v[84:85]
	v_rcp_f32_e32 v86, v86
	v_rcp_f32_e32 v87, v87
	v_rcp_f32_e32 v92, v92
	v_rcp_f32_e32 v93, v93
	v_pk_mul_f32 v[86:87], v[56:57], v[86:87]
	v_pk_mul_f32 v[92:93], v[58:59], v[92:93]
	v_cvt_pk_bf16_f32 v32, v86, v87
	v_cvt_pk_bf16_f32 v33, v92, v93
	ds_write_b64 v95, v[32:33] offset:40960
	v_pk_mul_f32 v[76:77], v[44:45], v[44:45]
	v_pk_mul_f32 v[78:79], v[46:47], v[46:47]
	v_pk_fma_f32 v[76:77], v[76:77], v[80:81], v[82:83]
	v_pk_fma_f32 v[78:79], v[78:79], v[80:81], v[82:83]
	v_pk_mul_f32 v[76:77], v[44:45], v[76:77]
	v_pk_mul_f32 v[78:79], v[46:47], v[78:79]
	v_exp_f32_e32 v76, v76
	v_exp_f32_e32 v77, v77
	v_exp_f32_e32 v78, v78
	v_exp_f32_e32 v79, v79
	v_pk_add_f32 v[76:77], v[76:77], v[84:85]
	v_pk_add_f32 v[78:79], v[78:79], v[84:85]
	v_rcp_f32_e32 v76, v76
	v_rcp_f32_e32 v77, v77
	v_rcp_f32_e32 v78, v78
	v_rcp_f32_e32 v79, v79
	v_pk_mul_f32 v[76:77], v[44:45], v[76:77]
	v_pk_mul_f32 v[78:79], v[46:47], v[78:79]
	v_cvt_pk_bf16_f32 v32, v76, v77
	v_cvt_pk_bf16_f32 v33, v78, v79
	ds_write_b64 v95, v[32:33] offset:49152
	v_pk_mul_f32 v[86:87], v[40:41], v[40:41]
	v_pk_mul_f32 v[92:93], v[42:43], v[42:43]
	v_pk_fma_f32 v[86:87], v[86:87], v[80:81], v[82:83]
	v_pk_fma_f32 v[92:93], v[92:93], v[80:81], v[82:83]
	v_pk_mul_f32 v[86:87], v[40:41], v[86:87]
	v_pk_mul_f32 v[92:93], v[42:43], v[92:93]
	v_exp_f32_e32 v86, v86
	v_exp_f32_e32 v87, v87
	v_exp_f32_e32 v92, v92
	v_exp_f32_e32 v93, v93
	v_pk_add_f32 v[86:87], v[86:87], v[84:85]
	v_pk_add_f32 v[92:93], v[92:93], v[84:85]
	v_rcp_f32_e32 v86, v86
	v_rcp_f32_e32 v87, v87
	v_rcp_f32_e32 v92, v92
	v_rcp_f32_e32 v93, v93
	v_pk_mul_f32 v[86:87], v[40:41], v[86:87]
	v_pk_mul_f32 v[92:93], v[42:43], v[92:93]
	v_cvt_pk_bf16_f32 v32, v86, v87
	v_cvt_pk_bf16_f32 v33, v92, v93
	ds_write_b64 v95, v[32:33] offset:57344
	v_lshl_add_u32 v32, v186, 4, 0
	v_lshrrev_b32_e32 v94, 1, v186
	v_and_b32_e32 v94, 0x70, v94
	v_xor_b32_e32 v32, v94, v32
	s_waitcnt lgkmcnt(0)
	s_barrier
	ds_read_b128 v[32:35], v32
	s_waitcnt lgkmcnt(0)
	global_store_dwordx4 v[36:37], v[32:35], off
	s_nop 1
	v_lshl_add_u32 v32, v189, 4, 0
	v_lshrrev_b32_e32 v94, 1, v189
	v_and_b32_e32 v94, 0x70, v94
	v_xor_b32_e32 v32, v94, v32
	ds_read_b128 v[32:35], v32
	s_waitcnt lgkmcnt(0)
	global_store_dwordx4 v[38:39], v[32:35], off
	s_nop 1
	v_lshl_add_u32 v32, v190, 4, 0
	v_lshrrev_b32_e32 v94, 1, v190
	v_and_b32_e32 v94, 0x70, v94
	v_xor_b32_e32 v32, v94, v32
	ds_read_b128 v[32:35], v32
	v_add_co_u32_e32 v38, vcc, s36, v36
	s_nop 1
	v_addc_co_u32_e32 v39, vcc, 0, v37, vcc
	s_waitcnt lgkmcnt(0)
	global_store_dwordx4 v[38:39], v[32:35], off
	v_add_co_u32_e32 v38, vcc, s37, v36
	s_nop 0
	v_lshl_add_u32 v32, v191, 4, 0
	v_lshrrev_b32_e32 v94, 1, v191
	v_and_b32_e32 v94, 0x70, v94
	v_xor_b32_e32 v32, v94, v32
	ds_read_b128 v[32:35], v32
	v_addc_co_u32_e32 v39, vcc, 0, v37, vcc
	s_waitcnt lgkmcnt(0)
	global_store_dwordx4 v[38:39], v[32:35], off
	s_nop 1
	v_lshl_add_u32 v32, v192, 4, 0
	v_lshrrev_b32_e32 v94, 1, v192
	v_and_b32_e32 v94, 0x70, v94
	v_xor_b32_e32 v32, v94, v32
	ds_read_b128 v[32:35], v32
	v_add_co_u32_e32 v38, vcc, s38, v36
	s_nop 1
	v_addc_co_u32_e32 v39, vcc, 0, v37, vcc
	s_waitcnt lgkmcnt(0)
	global_store_dwordx4 v[38:39], v[32:35], off
	v_add_co_u32_e32 v38, vcc, s39, v36
	s_nop 0
	v_lshl_add_u32 v32, v193, 4, 0
	v_lshrrev_b32_e32 v94, 1, v193
	v_and_b32_e32 v94, 0x70, v94
	v_xor_b32_e32 v32, v94, v32
	ds_read_b128 v[32:35], v32
	v_addc_co_u32_e32 v39, vcc, 0, v37, vcc
	s_waitcnt lgkmcnt(0)
	global_store_dwordx4 v[38:39], v[32:35], off
	s_nop 1
	v_lshl_add_u32 v32, v194, 4, 0
	v_lshrrev_b32_e32 v94, 1, v194
	v_and_b32_e32 v94, 0x70, v94
	v_xor_b32_e32 v32, v94, v32
	ds_read_b128 v[32:35], v32
	v_add_co_u32_e32 v38, vcc, 0xc000, v36
	s_nop 1
	v_addc_co_u32_e32 v39, vcc, 0, v37, vcc
	s_waitcnt lgkmcnt(0)
	global_store_dwordx4 v[38:39], v[32:35], off
	v_add_co_u32_e32 v36, vcc, 0xe000, v36
	s_nop 0
	v_lshl_add_u32 v32, v195, 4, 0
	v_lshrrev_b32_e32 v94, 1, v195
	v_and_b32_e32 v94, 0x70, v94
	v_xor_b32_e32 v32, v94, v32
	ds_read_b128 v[32:35], v32
	v_addc_co_u32_e32 v37, vcc, 0, v37, vcc
	s_and_b64 vcc, exec, s[6:7]
	s_waitcnt lgkmcnt(0)
	global_store_dwordx4 v[36:37], v[32:35], off
	s_barrier
	s_cbranch_vccnz .LBB0_503

.LBB0_498:
	v_and_b32_e32 v38, 63, v157
	s_cmp_gt_u32 s23, 63
	s_waitcnt lgkmcnt(0)
	s_barrier
	s_cbranch_scc1 .LBB0_501
	v_lshlrev_b32_e32 v32, 3, v38
	v_lshl_or_b32 v32, s45, 9, v32
	global_load_dwordx2 v[32:33], v32, s[88:89]
	v_mov_b32_e32 v36, 0
	v_lshlrev_b32_e32 v39, 1, v38
	v_lshlrev_b32_e32 v44, 2, v38
	s_mov_b32 s0, -16
	s_mov_b32 s23, 0
	v_mov_b32_e32 v37, v36
	s_waitcnt vmcnt(0)
	v_pk_mov_b32 v[34:35], v[32:33], v[32:33] op_sel:[1,0]

.Lscan_loop:
	s_waitcnt lgkmcnt(8)
	ds_read_b32 v55, v45 offset:2048
	ds_read_b32 v56, v45 offset:2304
	ds_read_b32 v57, v45 offset:2560
	ds_read_b32 v58, v45 offset:2816
	ds_read_b32 v59, v45 offset:3072
	ds_read_b32 v60, v45 offset:3328
	ds_read_b32 v61, v45 offset:3584
	ds_read_b32 v62, v45 offset:3840
	v_cvt_pk_bf16_f32 v161, v36, v37
	v_fma_f32 v159, v32, v36, v46
	v_fma_f32 v160, v32, v37, v47
	ds_write_b16 v50, v161
	ds_write_b16_d16_hi v50, v161 offset:128
	v_fma_f32 v157, -v33, v37, v159
	v_fma_f32 v158, v33, v36, v160
	v_cvt_pk_bf16_f32 v161, v157, v158
	v_fma_f32 v159, v32, v157, v48
	v_fma_f32 v160, v32, v158, v49
	ds_write_b16 v50, v161 offset:528
	ds_write_b16_d16_hi v50, v161 offset:656
	v_fma_f32 v36, -v33, v158, v159
	v_fma_f32 v37, v33, v157, v160
	v_cvt_pk_bf16_f32 v161, v36, v37
	v_fma_f32 v159, v32, v36, v51
	v_fma_f32 v160, v32, v37, v52
	ds_write_b16 v50, v161 offset:1056
	ds_write_b16_d16_hi v50, v161 offset:1184
	v_fma_f32 v157, -v33, v37, v159
	v_fma_f32 v158, v33, v36, v160
	v_cvt_pk_bf16_f32 v161, v157, v158
	v_fma_f32 v159, v32, v157, v53
	v_fma_f32 v160, v32, v158, v54
	ds_write_b16 v50, v161 offset:1584
	ds_write_b16_d16_hi v50, v161 offset:1712
	v_fma_f32 v36, -v33, v158, v159
	v_fma_f32 v37, v33, v157, v160
	s_waitcnt lgkmcnt(8)
	ds_read_b32 v46, v45 offset:4096
	ds_read_b32 v47, v45 offset:4352
	ds_read_b32 v48, v45 offset:4608
	ds_read_b32 v49, v45 offset:4864
	ds_read_b32 v51, v45 offset:5120
	ds_read_b32 v52, v45 offset:5376
	ds_read_b32 v53, v45 offset:5632
	ds_read_b32 v54, v45 offset:5888
	v_cvt_pk_bf16_f32 v161, v36, v37
	v_fma_f32 v159, v32, v36, v55
	v_fma_f32 v160, v32, v37, v56
	ds_write_b16 v50, v161 offset:2112
	ds_write_b16_d16_hi v50, v161 offset:2240
	v_fma_f32 v157, -v33, v37, v159
	v_fma_f32 v158, v33, v36, v160
	v_cvt_pk_bf16_f32 v161, v157, v158
	v_fma_f32 v159, v32, v157, v57
	v_fma_f32 v160, v32, v158, v58
	ds_write_b16 v50, v161 offset:2640
	ds_write_b16_d16_hi v50, v161 offset:2768
	v_fma_f32 v36, -v33, v158, v159
	v_fma_f32 v37, v33, v157, v160
	v_cvt_pk_bf16_f32 v161, v36, v37
	v_fma_f32 v159, v32, v36, v59
	v_fma_f32 v160, v32, v37, v60
	ds_write_b16 v50, v161 offset:3168
	ds_write_b16_d16_hi v50, v161 offset:3296
	v_fma_f32 v157, -v33, v37, v159
	v_fma_f32 v158, v33, v36, v160
	v_cvt_pk_bf16_f32 v161, v157, v158
	v_fma_f32 v159, v32, v157, v61
	v_fma_f32 v160, v32, v158, v62
	ds_write_b16 v50, v161 offset:3696
	ds_write_b16_d16_hi v50, v161 offset:3824
	v_fma_f32 v36, -v33, v158, v159
	v_fma_f32 v37, v33, v157, v160
	s_waitcnt lgkmcnt(8)
	ds_read_b32 v55, v45 offset:6144
	ds_read_b32 v56, v45 offset:6400
	ds_read_b32 v57, v45 offset:6656
	ds_read_b32 v58, v45 offset:6912
	ds_read_b32 v59, v45 offset:7168
	ds_read_b32 v60, v45 offset:7424
	ds_read_b32 v61, v45 offset:7680
	ds_read_b32 v62, v45 offset:7936
	v_cvt_pk_bf16_f32 v161, v36, v37
	v_fma_f32 v159, v32, v36, v46
	v_fma_f32 v160, v32, v37, v47
	ds_write_b16 v50, v161 offset:4224
	ds_write_b16_d16_hi v50, v161 offset:4352
	v_fma_f32 v157, -v33, v37, v159
	v_fma_f32 v158, v33, v36, v160
	v_cvt_pk_bf16_f32 v161, v157, v158
	v_fma_f32 v159, v32, v157, v48
	v_fma_f32 v160, v32, v158, v49
	ds_write_b16 v50, v161 offset:4752
	ds_write_b16_d16_hi v50, v161 offset:4880
	v_fma_f32 v36, -v33, v158, v159
	v_fma_f32 v37, v33, v157, v160
	v_cvt_pk_bf16_f32 v161, v36, v37
	v_fma_f32 v159, v32, v36, v51
	v_fma_f32 v160, v32, v37, v52
	ds_write_b16 v50, v161 offset:5280
	ds_write_b16_d16_hi v50, v161 offset:5408
	v_fma_f32 v157, -v33, v37, v159
	v_fma_f32 v158, v33, v36, v160
	v_cvt_pk_bf16_f32 v161, v157, v158
	v_fma_f32 v159, v32, v157, v53
	v_fma_f32 v160, v32, v158, v54
	ds_write_b16 v50, v161 offset:5808
	ds_write_b16_d16_hi v50, v161 offset:5936
	v_fma_f32 v36, -v33, v158, v159
	v_fma_f32 v37, v33, v157, v160
	s_waitcnt lgkmcnt(8)
	ds_read_b32 v46, v45 offset:8192
	ds_read_b32 v47, v45 offset:8448
	ds_read_b32 v48, v45 offset:8704
	ds_read_b32 v49, v45 offset:8960
	ds_read_b32 v51, v45 offset:9216
	ds_read_b32 v52, v45 offset:9472
	ds_read_b32 v53, v45 offset:9728
	ds_read_b32 v54, v45 offset:9984
	v_cvt_pk_bf16_f32 v161, v36, v37
	v_fma_f32 v159, v32, v36, v55
	v_fma_f32 v160, v32, v37, v56
	ds_write_b16 v50, v161 offset:6336
	ds_write_b16_d16_hi v50, v161 offset:6464
	v_fma_f32 v157, -v33, v37, v159
	v_fma_f32 v158, v33, v36, v160
	v_cvt_pk_bf16_f32 v161, v157, v158
	v_fma_f32 v159, v32, v157, v57
	v_fma_f32 v160, v32, v158, v58
	ds_write_b16 v50, v161 offset:6864
	ds_write_b16_d16_hi v50, v161 offset:6992
	v_fma_f32 v36, -v33, v158, v159
	v_fma_f32 v37, v33, v157, v160
	v_cvt_pk_bf16_f32 v161, v36, v37
	v_fma_f32 v159, v32, v36, v59
	v_fma_f32 v160, v32, v37, v60
	ds_write_b16 v50, v161 offset:7392
	ds_write_b16_d16_hi v50, v161 offset:7520
	v_fma_f32 v157, -v33, v37, v159
	v_fma_f32 v158, v33, v36, v160
	v_cvt_pk_bf16_f32 v161, v157, v158
	v_fma_f32 v159, v32, v157, v61
	v_fma_f32 v160, v32, v158, v62
	ds_write_b16 v50, v161 offset:7920
	ds_write_b16_d16_hi v50, v161 offset:8048
	v_fma_f32 v36, -v33, v158, v159
	v_fma_f32 v37, v33, v157, v160
	v_add_u32_e32 v45, 0x2000, v45
	v_add_u32_e32 v50, 0x2000, v50
	s_add_i32 s0, s0, 16
	s_cmpk_lt_u32 s0, 0x70
	s_cbranch_scc1 .Lscan_loop
	s_waitcnt lgkmcnt(0)
